# attention, XCD-local mode: the 24 short context-query GQA units ride on second-round long tickets 64..87 (run next without a ticket) instead of being handed out after the long ones
# speedup vs baseline: 1.0097x; 1.0097x over previous
; template <int Q>
; DI void attn_queue(const Params& p, int l, char* smem, int* s_unit, int cb) {
;     ...
;     const int total = (Q == 0) ? (ctxu ? 576 : 512) : (Q == 1) ? (ctxu ? 960 : 768) : 768;
;     ...
;         } else if (Q == 1) {
;             int b, head, qt, t1 = 0, n1 = 36; bool cgrp = false;
;             if (u < 768) { b = u / 96; head = (u >> 4) % 6; qt = u & 15; }
;             else if (u < 864) { const int v = u - 768; b = v / 12; head = (v >> 1) % 6; qt = 16 + (v & 1); t1 = 32; n1 = 4; }
;             else { const int v = u - 864; b = v / 12; head = (v >> 1) % 6; qt = 16 + (v & 1); t1 = 32; n1 = 4; cgrp = true; }
;             int qcol, kcol, vfeat, gcol, mixcol;
;             if (!cgrp) { const int kv = head / 3; qcol = 1024 + head * 64; kcol = 1408 + kv * 64; vfeat = 256 + kv * 64; gcol = 1664 + head * 64; mixcol = 256 + head * 64; }
;             else { qcol = 2048 + head * 64; kcol = 2432 + head * 64; vfeat = 384 + head * 64; gcol = 3200 + head * 64; mixcol = 640 + head * 64; }
;             attn_unit<1>(p, l, b, head, qt, qcol, kcol, vfeat, gcol, mixcol, t1, n1, 0, 0, smem);
.LBB0_84:
	s_and_b64 s[4:5], s[44:45], exec
	s_movk_i32 s4, 0x3c0
	s_cselect_b32 s28, s4, 0x300
	s_movk_i32 s61, 0x800
	v_writelane_b32 v255, 0, 45
	s_branch .LBB0_86

; template <int Q>
; DI void attn_queue(const Params& p, int l, char* smem, int* s_unit, int cb) {
;     ...
;     for (;;) {
;         if (threadIdx.x == 0) *s_unit = (int)atomicAdd(p.ctr + cb + l * 4 + Q, 1u);
;         __syncthreads();
;         const int u = *s_unit;
;         __syncthreads();
;         if (u >= total) break;
;         if (Q == 0) {
;             int b, head, qt, t1 = 0, n1 = 36;
;             if (u < 512) { b = u >> 6; head = (u >> 4) & 3; qt = u & 15; }
;             else { const int v = u - 512; b = v >> 3; head = (v >> 1) & 3; qt = 16 + (v & 1); t1 = 32; n1 = 4; }
;             attn_unit<0>(p, l, b, head, qt, head * 64, 256 + head * 64, head * 64, 768 + head * 64, head * 64, t1, n1, 0, 0, smem);
;         } else if (Q == 1) {
;             int b, head, qt, t1 = 0, n1 = 36; bool cgrp = false;
;             if (u < 768) { b = u / 96; head = (u >> 4) % 6; qt = u & 15; }
;             else if (u < 864) { const int v = u - 768; b = v / 12; head = (v >> 1) % 6; qt = 16 + (v & 1); t1 = 32; n1 = 4; }
;             else { const int v = u - 864; b = v / 12; head = (v >> 1) % 6; qt = 16 + (v & 1); t1 = 32; n1 = 4; cgrp = true; }
;             int qcol, kcol, vfeat, gcol, mixcol;
;             if (!cgrp) { const int kv = head / 3; qcol = 1024 + head * 64; kcol = 1408 + kv * 64; vfeat = 256 + kv * 64; gcol = 1664 + head * 64; mixcol = 256 + head * 64; }
;             else { qcol = 2048 + head * 64; kcol = 2432 + head * 64; vfeat = 384 + head * 64; gcol = 3200 + head * 64; mixcol = 640 + head * 64; }
;             attn_unit<1>(p, l, b, head, qt, qcol, kcol, vfeat, gcol, mixcol, t1, n1, 0, 0, smem);
.LBB0_86:
	s_and_saveexec_b64 s[4:5], s[54:55]
	s_cbranch_execz .LBB0_90
	s_mov_b64 s[8:9], exec
	v_mbcnt_lo_u32_b32 v0, s8, 0
	v_mbcnt_hi_u32_b32 v0, s9, v0
	v_cmp_eq_u32_e32 vcc, 0, v0
	s_and_saveexec_b64 s[6:7], vcc
	s_cbranch_execz .LBB0_89
	ds_read_b32 v2, v193 offset:8
	s_load_dwordx2 s[34:35], s[0:1], 0x100
	s_lshl_b64 s[40:41], s[48:49], 2
	s_waitcnt lgkmcnt(0)
	s_add_u32 s34, s34, s40
	s_addc_u32 s35, s35, s41
	v_readfirstlane_b32 s40, v2
	s_nop 0
	s_cmp_eq_u32 s40, 0
	s_cbranch_scc1 .Lq1_glob
	v_readlane_b32 s9, v255, 45
	s_nop 0
	s_cmp_eq_u32 s9, 0
	s_cbranch_scc1 .Lq1_norm
	s_add_i32 s34, s9, -1
	v_writelane_b32 v255, 0, 45
	s_branch .Lq1_pub
.Lq1_norm:
	v_readlane_b32 s8, v254, 0
	s_nop 0
	s_and_b32 s8, s8, 7
	s_lshl_b32 s9, s8, 8
	s_lshl_b32 s40, s60, 4
	s_add_i32 s9, s9, s40
	s_addk_i32 s9, 0x2424
	s_add_u32 s34, s68, s9
	s_addc_u32 s35, s69, 0
	v_mov_b32_e32 v1, 1
	global_atomic_add v1, v193, v1, s[34:35] sc0
	s_waitcnt vmcnt(0)
	v_readfirstlane_b32 s9, v1
	s_nop 0
	s_lshr_b32 s40, s28, 3
	s_mul_i32 s35, s8, 12
	s_mul_i32 s34, s8, 0x60
	s_add_i32 s34, s34, s9
	s_cmp_lt_u32 s9, 0x60
	s_cselect_b32 s34, s34, s28
	s_cmp_lt_u32 s9, 64
	s_cbranch_scc1 .Lq1_pub
	s_add_i32 s9, s9, 32
	s_cmp_lt_u32 s9, s40
	s_cbranch_scc0 .Lq1_pub
	s_add_i32 s35, s35, s9
	s_add_i32 s8, s35, 0x2a0
	s_addk_i32 s35, 0x2f4
	s_cmp_lt_u32 s9, 0x6c
	s_cselect_b32 s8, s8, s35
	s_add_i32 s8, s8, 1
	v_writelane_b32 v255, s8, 45
.Lq1_pub:
	v_mov_b32_e32 v1, s34
	s_branch .LBB0_89
